# cache-aware phase order: Res reversed + mid stores plain + conv4/scan remapped to group-major reverse order
# speedup vs baseline: 1.0097x; 1.0068x over previous
; #define LAS __attribute__((address_space(3)))
; __device__ __forceinline__ u32x4 pack8(const f32x4 a, const f32x4 b) { u32x4 w; w.x = cvt_pk_rtz(a[0], a[1]); w.y = cvt_pk_rtz(a[2], a[3]); w.z = cvt_pk_rtz(b[0], b[1]); w.w = cvt_pk_rtz(b[2], b[3]); return w; }
; template <class T> __device__ __forceinline__ T* at(const void* base, unsigned byteoff) { return (T*)((char*)base + byteoff); }
;     __device__ __forceinline__ void operator()(const Acc& acc, const pg8::Unit& u, int wr, int wc, int fr, int fq, LAS float* rcache, int& cached_pm) const {
;         const int row0 = u.pm * 256 + wr * 64 + fr, col0 = u.pn * 128 + wc * 32 + 8 * fq;
;         float rs8[8]; get_rstd8(ssq, u.pm, row0, fr, fq, rcache, cached_pm, rs8);
; #pragma unroll
;         for (int ai = 0; ai < 2; ++ai)
; #pragma unroll
;             for (int m = 0; m < 4; ++m) {
;                 const int row = row0 + ai * 128 + m * 16; const float rs = rs8[ai * 4 + m], nrl = rs * -1.4426950408889634f, rs2 = rs * rs;
;                 f32x4 o[2];
; #pragma unroll
;                 for (int n = 0; n < 2; ++n) { const f32x4 gv = acc[ai][0][m][n], uv = acc[ai][1][m][n]; const f32x4 t = gv * nrl; f32x4 e;
; #pragma unroll
;                     for (int j = 0; j < 4; ++j) e[j] = __builtin_amdgcn_exp2f(t[j]);
;                     e = e + 1.0f; f32x4 r;
; #pragma unroll
;                     for (int j = 0; j < 4; ++j) r[j] = __builtin_amdgcn_rcpf(e[j]);
;                     o[n] = ((gv * uv) * rs2) * r; }
;     ...
;                 *at<u32x4>(O, (unsigned)(row * DFF + col0) * 2u) = pack8(o[0], o[1]) & 0xFFF8FFF8u;
;     ...
;                 __builtin_nontemporal_store(pack8(o[0], o[1]), at<u32x4>(O, (unsigned)(row * DFF + col0) * 2u));
.LBB0_94:
	s_waitcnt lgkmcnt(0)
	v_mul_f32_e32 v132, 0xbfb8aa3b, v160
	v_pk_mul_f32 v[134:135], v[124:125], v[132:133] op_sel_hi:[1,0]
	v_pk_mul_f32 v[136:137], v[122:123], v[132:133] op_sel_hi:[1,0]
	v_lshl_or_b32 v133, s67, 7, v171
	v_pk_mul_f32 v[122:123], v[126:127], v[122:123]
	v_pk_mul_f32 v[126:127], v[120:121], v[132:133] op_sel_hi:[1,0]
	v_exp_f32_e32 v136, v136
	v_exp_f32_e32 v126, v126
	v_exp_f32_e32 v127, v127
	v_exp_f32_e32 v134, v134
	v_exp_f32_e32 v135, v135
	v_exp_f32_e32 v137, v137
	v_pk_mul_f32 v[124:125], v[128:129], v[124:125]
	v_pk_mul_f32 v[128:129], v[118:119], v[132:133] op_sel_hi:[1,0]
	v_pk_add_f32 v[126:127], v[126:127], 1.0 op_sel_hi:[1,0]
	v_pk_add_f32 v[134:135], v[134:135], 1.0 op_sel_hi:[1,0]
	v_pk_add_f32 v[136:137], v[136:137], 1.0 op_sel_hi:[1,0]
	v_exp_f32_e32 v128, v128
	v_exp_f32_e32 v129, v129
	v_rcp_f32_e32 v126, v126
	v_rcp_f32_e32 v127, v127
	v_rcp_f32_e32 v136, v136
	v_rcp_f32_e32 v137, v137
	v_rcp_f32_e32 v134, v134
	v_rcp_f32_e32 v135, v135
	v_mul_f32_e32 v140, v160, v160
	v_pk_mul_f32 v[116:117], v[116:117], v[120:121]
	v_pk_mul_f32 v[122:123], v[122:123], v[140:141] op_sel_hi:[1,0]
	v_pk_mul_f32 v[116:117], v[116:117], v[140:141] op_sel_hi:[1,0]
	v_pk_mul_f32 v[124:125], v[124:125], v[140:141] op_sel_hi:[1,0]
	v_pk_add_f32 v[128:129], v[128:129], 1.0 op_sel_hi:[1,0]
	v_pk_mul_f32 v[120:121], v[116:117], v[126:127]
	v_pk_mul_f32 v[124:125], v[124:125], v[134:135]
	v_pk_mul_f32 v[122:123], v[122:123], v[136:137]
	v_rcp_f32_e32 v128, v128
	v_rcp_f32_e32 v129, v129
	v_pk_mul_f32 v[114:115], v[114:115], v[118:119]
	v_cvt_pk_bf16_f32 v119, v120, v121
	v_mul_f32_e32 v120, 0xbfb8aa3b, v161
	v_cvt_pk_bf16_f32 v116, v122, v123
	v_cvt_pk_bf16_f32 v117, v124, v125
	v_pk_mul_f32 v[122:123], v[112:113], v[120:121] op_sel_hi:[1,0]
	v_pk_mul_f32 v[124:125], v[110:111], v[120:121] op_sel_hi:[1,0]
	v_pk_mul_f32 v[108:109], v[108:109], v[112:113]
	v_pk_mul_f32 v[106:107], v[106:107], v[110:111]
	v_pk_mul_f32 v[110:111], v[104:105], v[120:121] op_sel_hi:[1,0]
	v_pk_mul_f32 v[112:113], v[102:103], v[120:121] op_sel_hi:[1,0]
	v_exp_f32_e32 v110, v110
	v_exp_f32_e32 v112, v112
	v_exp_f32_e32 v111, v111
	v_exp_f32_e32 v113, v113
	v_pk_mul_f32 v[114:115], v[114:115], v[140:141] op_sel_hi:[1,0]
	v_exp_f32_e32 v124, v124
	v_exp_f32_e32 v122, v122
	v_exp_f32_e32 v123, v123
	v_exp_f32_e32 v125, v125
	v_pk_mul_f32 v[114:115], v[114:115], v[128:129]
	s_movk_i32 s2, 0xb00
	v_cvt_pk_bf16_f32 v118, v114, v115
	v_mul_lo_u32 v114, v173, s2
	v_add_lshl_u32 v114, v114, v133, 1
	v_pk_add_f32 v[110:111], v[110:111], 1.0 op_sel_hi:[1,0]
	v_pk_add_f32 v[112:113], v[112:113], 1.0 op_sel_hi:[1,0]
	global_store_dwordx4 v114, v[116:119], s[24:25]
	v_rcp_f32_e32 v112, v112
	v_rcp_f32_e32 v113, v113
	v_pk_add_f32 v[118:119], v[122:123], 1.0 op_sel_hi:[1,0]
	v_pk_add_f32 v[122:123], v[124:125], 1.0 op_sel_hi:[1,0]
	v_rcp_f32_e32 v110, v110
	v_rcp_f32_e32 v111, v111
	v_rcp_f32_e32 v122, v122
	v_rcp_f32_e32 v123, v123
	v_mul_f32_e32 v116, v161, v161
	v_pk_mul_f32 v[100:101], v[100:101], v[104:105]
	v_pk_mul_f32 v[98:99], v[98:99], v[102:103]
	v_pk_mul_f32 v[100:101], v[100:101], v[116:117] op_sel_hi:[1,0]
	v_pk_mul_f32 v[98:99], v[98:99], v[116:117] op_sel_hi:[1,0]
	v_pk_mul_f32 v[106:107], v[106:107], v[116:117] op_sel_hi:[1,0]
	v_pk_mul_f32 v[102:103], v[100:101], v[110:111]
	v_pk_mul_f32 v[100:101], v[98:99], v[112:113]
	v_pk_mul_f32 v[106:107], v[106:107], v[122:123]
	v_cvt_pk_bf16_f32 v100, v100, v101
	v_cvt_pk_bf16_f32 v101, v102, v103
	v_add_u32_e32 v103, 0x16000, v114
	v_mul_f32_e32 v102, 0xbfb8aa3b, v158
	v_rcp_f32_e32 v118, v118
	v_rcp_f32_e32 v119, v119
	v_cvt_pk_bf16_f32 v98, v106, v107
	v_pk_mul_f32 v[104:105], v[96:97], v[102:103] op_sel_hi:[1,0]
	v_pk_mul_f32 v[106:107], v[94:95], v[102:103] op_sel_hi:[1,0]
	v_pk_mul_f32 v[92:93], v[92:93], v[96:97]
	v_pk_mul_f32 v[90:91], v[90:91], v[94:95]
	v_pk_mul_f32 v[94:95], v[88:89], v[102:103] op_sel_hi:[1,0]
	v_pk_mul_f32 v[96:97], v[86:87], v[102:103] op_sel_hi:[1,0]
	v_exp_f32_e32 v94, v94
	v_exp_f32_e32 v96, v96
	v_exp_f32_e32 v95, v95
	v_exp_f32_e32 v97, v97
	v_exp_f32_e32 v106, v106
	v_exp_f32_e32 v104, v104
	v_exp_f32_e32 v105, v105
	v_exp_f32_e32 v107, v107
	v_pk_mul_f32 v[108:109], v[108:109], v[116:117] op_sel_hi:[1,0]
	v_pk_add_f32 v[94:95], v[94:95], 1.0 op_sel_hi:[1,0]
	v_pk_mul_f32 v[108:109], v[108:109], v[118:119]
	v_pk_add_f32 v[96:97], v[96:97], 1.0 op_sel_hi:[1,0]
	v_cvt_pk_bf16_f32 v99, v108, v109
	global_store_dwordx4 v103, v[98:101], s[24:25]
	v_rcp_f32_e32 v96, v96
	v_rcp_f32_e32 v97, v97
	v_pk_add_f32 v[100:101], v[104:105], 1.0 op_sel_hi:[1,0]
	v_pk_add_f32 v[104:105], v[106:107], 1.0 op_sel_hi:[1,0]
	v_rcp_f32_e32 v94, v94
	v_rcp_f32_e32 v95, v95
	v_rcp_f32_e32 v104, v104
	v_rcp_f32_e32 v105, v105
	v_mul_f32_e32 v98, v158, v158
	v_pk_mul_f32 v[84:85], v[84:85], v[88:89]
	v_pk_mul_f32 v[82:83], v[82:83], v[86:87]
	v_pk_mul_f32 v[84:85], v[84:85], v[98:99] op_sel_hi:[1,0]
	v_pk_mul_f32 v[82:83], v[82:83], v[98:99] op_sel_hi:[1,0]
	v_pk_mul_f32 v[90:91], v[90:91], v[98:99] op_sel_hi:[1,0]
	v_pk_mul_f32 v[86:87], v[84:85], v[94:95]
	v_pk_mul_f32 v[84:85], v[82:83], v[96:97]
	v_pk_mul_f32 v[90:91], v[90:91], v[104:105]
	v_cvt_pk_bf16_f32 v84, v84, v85
	v_cvt_pk_bf16_f32 v85, v86, v87
	v_add_u32_e32 v87, 0x2c000, v114
	v_mul_f32_e32 v86, 0xbfb8aa3b, v159
	v_rcp_f32_e32 v100, v100
	v_rcp_f32_e32 v101, v101
	v_cvt_pk_bf16_f32 v82, v90, v91
	v_pk_mul_f32 v[88:89], v[78:79], v[86:87] op_sel_hi:[1,0]
	v_pk_mul_f32 v[90:91], v[76:77], v[86:87] op_sel_hi:[1,0]
	v_pk_mul_f32 v[74:75], v[74:75], v[78:79]
	v_pk_mul_f32 v[72:73], v[72:73], v[76:77]
; __device__ __forceinline__ u32x4 pack8(const f32x4 a, const f32x4 b) { u32x4 w; w.x = cvt_pk_rtz(a[0], a[1]); w.y = cvt_pk_rtz(a[2], a[3]); w.z = cvt_pk_rtz(b[0], b[1]); w.w = cvt_pk_rtz(b[2], b[3]); return w; }
; template <class T> __device__ __forceinline__ T* at(const void* base, unsigned byteoff) { return (T*)((char*)base + byteoff); }
;     __device__ __forceinline__ void operator()(const Acc& acc, const pg8::Unit& u, int wr, int wc, int fr, int fq, LAS float* rcache, int& cached_pm) const {
;     ...
;             for (int m = 0; m < 4; ++m) {
;                 const int row = row0 + ai * 128 + m * 16; const float rs = rs8[ai * 4 + m], nrl = rs * -1.4426950408889634f, rs2 = rs * rs;
;                 f32x4 o[2];
; #pragma unroll
;                 for (int n = 0; n < 2; ++n) { const f32x4 gv = acc[ai][0][m][n], uv = acc[ai][1][m][n]; const f32x4 t = gv * nrl; f32x4 e;
; #pragma unroll
;                     for (int j = 0; j < 4; ++j) e[j] = __builtin_amdgcn_exp2f(t[j]);
;                     e = e + 1.0f; f32x4 r;
; #pragma unroll
;                     for (int j = 0; j < 4; ++j) r[j] = __builtin_amdgcn_rcpf(e[j]);
;                     o[n] = ((gv * uv) * rs2) * r; }
;     ...
;                 *at<u32x4>(O, (unsigned)(row * DFF + col0) * 2u) = pack8(o[0], o[1]) & 0xFFF8FFF8u;
;     ...
;                 __builtin_nontemporal_store(pack8(o[0], o[1]), at<u32x4>(O, (unsigned)(row * DFF + col0) * 2u));
	v_pk_mul_f32 v[76:77], v[70:71], v[86:87] op_sel_hi:[1,0]
	v_pk_mul_f32 v[78:79], v[68:69], v[86:87] op_sel_hi:[1,0]
	v_exp_f32_e32 v76, v76
	v_exp_f32_e32 v78, v78
	v_exp_f32_e32 v77, v77
	v_exp_f32_e32 v79, v79
	v_exp_f32_e32 v90, v90
	v_exp_f32_e32 v88, v88
	v_exp_f32_e32 v89, v89
	v_exp_f32_e32 v91, v91
	v_pk_mul_f32 v[92:93], v[92:93], v[98:99] op_sel_hi:[1,0]
	v_pk_add_f32 v[76:77], v[76:77], 1.0 op_sel_hi:[1,0]
	v_pk_mul_f32 v[92:93], v[92:93], v[100:101]
	v_pk_add_f32 v[78:79], v[78:79], 1.0 op_sel_hi:[1,0]
	v_cvt_pk_bf16_f32 v83, v92, v93
	global_store_dwordx4 v87, v[82:85], s[24:25]
	v_rcp_f32_e32 v78, v78
	v_rcp_f32_e32 v79, v79
	v_pk_add_f32 v[84:85], v[88:89], 1.0 op_sel_hi:[1,0]
	v_pk_add_f32 v[88:89], v[90:91], 1.0 op_sel_hi:[1,0]
	v_rcp_f32_e32 v76, v76
	v_rcp_f32_e32 v77, v77
	v_rcp_f32_e32 v88, v88
	v_rcp_f32_e32 v89, v89
	v_mul_f32_e32 v82, v159, v159
	v_pk_mul_f32 v[66:67], v[66:67], v[70:71]
	v_pk_mul_f32 v[64:65], v[64:65], v[68:69]
	v_pk_mul_f32 v[66:67], v[66:67], v[82:83] op_sel_hi:[1,0]
	v_pk_mul_f32 v[64:65], v[64:65], v[82:83] op_sel_hi:[1,0]
	v_pk_mul_f32 v[72:73], v[72:73], v[82:83] op_sel_hi:[1,0]
	v_pk_mul_f32 v[68:69], v[66:67], v[76:77]
	v_pk_mul_f32 v[66:67], v[64:65], v[78:79]
	v_pk_mul_f32 v[72:73], v[72:73], v[88:89]
	v_cvt_pk_bf16_f32 v66, v66, v67
	v_cvt_pk_bf16_f32 v67, v68, v69
	v_add_u32_e32 v69, 0x42000, v114
	v_mul_f32_e32 v68, 0xbfb8aa3b, v138
	v_rcp_f32_e32 v84, v84
	v_rcp_f32_e32 v85, v85
	v_cvt_pk_bf16_f32 v64, v72, v73
	v_pk_mul_f32 v[70:71], v[62:63], v[68:69] op_sel_hi:[1,0]
	v_pk_mul_f32 v[72:73], v[60:61], v[68:69] op_sel_hi:[1,0]
	v_pk_mul_f32 v[58:59], v[58:59], v[62:63]
	v_pk_mul_f32 v[56:57], v[56:57], v[60:61]
	v_pk_mul_f32 v[60:61], v[54:55], v[68:69] op_sel_hi:[1,0]
	v_pk_mul_f32 v[62:63], v[52:53], v[68:69] op_sel_hi:[1,0]
	v_exp_f32_e32 v60, v60
	v_exp_f32_e32 v62, v62
	v_exp_f32_e32 v61, v61
	v_exp_f32_e32 v63, v63
	v_exp_f32_e32 v72, v72
	v_exp_f32_e32 v70, v70
	v_exp_f32_e32 v71, v71
	v_exp_f32_e32 v73, v73
	v_pk_mul_f32 v[74:75], v[74:75], v[82:83] op_sel_hi:[1,0]
	v_pk_add_f32 v[60:61], v[60:61], 1.0 op_sel_hi:[1,0]
	v_pk_mul_f32 v[74:75], v[74:75], v[84:85]
	v_pk_add_f32 v[62:63], v[62:63], 1.0 op_sel_hi:[1,0]
	v_cvt_pk_bf16_f32 v65, v74, v75
	global_store_dwordx4 v69, v[64:67], s[24:25]
	v_rcp_f32_e32 v62, v62
	v_rcp_f32_e32 v63, v63
	v_pk_add_f32 v[66:67], v[70:71], 1.0 op_sel_hi:[1,0]
	v_pk_add_f32 v[70:71], v[72:73], 1.0 op_sel_hi:[1,0]
	v_rcp_f32_e32 v60, v60
	v_rcp_f32_e32 v61, v61
	v_rcp_f32_e32 v70, v70
	v_rcp_f32_e32 v71, v71
	v_mul_f32_e32 v64, v138, v138
	v_pk_mul_f32 v[50:51], v[50:51], v[54:55]
	v_pk_mul_f32 v[48:49], v[48:49], v[52:53]
	v_pk_mul_f32 v[50:51], v[50:51], v[64:65] op_sel_hi:[1,0]
	v_pk_mul_f32 v[48:49], v[48:49], v[64:65] op_sel_hi:[1,0]
	v_pk_mul_f32 v[56:57], v[56:57], v[64:65] op_sel_hi:[1,0]
	v_pk_mul_f32 v[52:53], v[50:51], v[60:61]
	v_pk_mul_f32 v[50:51], v[48:49], v[62:63]
	v_pk_mul_f32 v[56:57], v[56:57], v[70:71]
	v_cvt_pk_bf16_f32 v50, v50, v51
	v_cvt_pk_bf16_f32 v51, v52, v53
	v_add_u32_e32 v53, 0xb0000, v114
	v_mul_f32_e32 v52, 0xbfb8aa3b, v139
	v_rcp_f32_e32 v66, v66
	v_rcp_f32_e32 v67, v67
	v_cvt_pk_bf16_f32 v48, v56, v57
	v_pk_mul_f32 v[54:55], v[46:47], v[52:53] op_sel_hi:[1,0]
	v_pk_mul_f32 v[56:57], v[44:45], v[52:53] op_sel_hi:[1,0]
	v_pk_mul_f32 v[42:43], v[42:43], v[46:47]
	v_pk_mul_f32 v[40:41], v[40:41], v[44:45]
	v_pk_mul_f32 v[44:45], v[38:39], v[52:53] op_sel_hi:[1,0]
	v_pk_mul_f32 v[46:47], v[36:37], v[52:53] op_sel_hi:[1,0]
	v_exp_f32_e32 v44, v44
	v_exp_f32_e32 v46, v46
	v_exp_f32_e32 v45, v45
	v_exp_f32_e32 v47, v47
	v_exp_f32_e32 v56, v56
	v_exp_f32_e32 v54, v54
	v_exp_f32_e32 v55, v55
	v_exp_f32_e32 v57, v57
	v_pk_mul_f32 v[58:59], v[58:59], v[64:65] op_sel_hi:[1,0]
	v_pk_add_f32 v[44:45], v[44:45], 1.0 op_sel_hi:[1,0]
	v_pk_mul_f32 v[58:59], v[58:59], v[66:67]
	v_pk_add_f32 v[46:47], v[46:47], 1.0 op_sel_hi:[1,0]
	v_cvt_pk_bf16_f32 v49, v58, v59
	global_store_dwordx4 v53, v[48:51], s[24:25]
	v_rcp_f32_e32 v46, v46
	v_rcp_f32_e32 v47, v47
	v_pk_add_f32 v[50:51], v[54:55], 1.0 op_sel_hi:[1,0]
	v_pk_add_f32 v[54:55], v[56:57], 1.0 op_sel_hi:[1,0]
	v_rcp_f32_e32 v44, v44
	v_rcp_f32_e32 v45, v45
	v_rcp_f32_e32 v54, v54
	v_rcp_f32_e32 v55, v55
	v_mul_f32_e32 v48, v139, v139
; __device__ __forceinline__ u32x4 pack8(const f32x4 a, const f32x4 b) { u32x4 w; w.x = cvt_pk_rtz(a[0], a[1]); w.y = cvt_pk_rtz(a[2], a[3]); w.z = cvt_pk_rtz(b[0], b[1]); w.w = cvt_pk_rtz(b[2], b[3]); return w; }
; #define PG8_BAR __builtin_amdgcn_s_barrier()
; template <class T> __device__ __forceinline__ T* at(const void* base, unsigned byteoff) { return (T*)((char*)base + byteoff); }
; template <class Epi>
; __device__ __forceinline__ void gemm_phase(LAS unsigned char* lds, const Gemm g, const StaticOrder& S, const Epi& E, int tid_) {
;     ...
;         if (!has_next) break;
; #pragma unroll
;         for (int a = 0; a < 2; ++a)
; #pragma unroll
;             for (int b = 0; b < 2; ++b)
; #pragma unroll
;                 for (int m = 0; m < 4; ++m)
; #pragma unroll
;                     for (int n = 0; n < 2; ++n) acc[a][b][m][n] = (f32x4){0.f, 0.f, 0.f, 0.f};
;         cur = nxt; cA = nA; cB = nB; ++ui;
;         if (wr == 1) PG8_BAR;
;     __device__ __forceinline__ void operator()(const Acc& acc, const pg8::Unit& u, int wr, int wc, int fr, int fq, LAS float* rcache, int& cached_pm) const {
;     ...
;             for (int m = 0; m < 4; ++m) {
;                 const int row = row0 + ai * 128 + m * 16; const float rs = rs8[ai * 4 + m], nrl = rs * -1.4426950408889634f, rs2 = rs * rs;
;                 f32x4 o[2];
; #pragma unroll
;                 for (int n = 0; n < 2; ++n) { const f32x4 gv = acc[ai][0][m][n], uv = acc[ai][1][m][n]; const f32x4 t = gv * nrl; f32x4 e;
; #pragma unroll
;                     for (int j = 0; j < 4; ++j) e[j] = __builtin_amdgcn_exp2f(t[j]);
;                     e = e + 1.0f; f32x4 r;
; #pragma unroll
;                     for (int j = 0; j < 4; ++j) r[j] = __builtin_amdgcn_rcpf(e[j]);
;                     o[n] = ((gv * uv) * rs2) * r; }
;     ...
;                 *at<u32x4>(O, (unsigned)(row * DFF + col0) * 2u) = pack8(o[0], o[1]) & 0xFFF8FFF8u;
;     ...
;                 __builtin_nontemporal_store(pack8(o[0], o[1]), at<u32x4>(O, (unsigned)(row * DFF + col0) * 2u));
	v_pk_mul_f32 v[34:35], v[34:35], v[38:39]
	v_pk_mul_f32 v[32:33], v[32:33], v[36:37]
	v_pk_mul_f32 v[34:35], v[34:35], v[48:49] op_sel_hi:[1,0]
	v_pk_mul_f32 v[32:33], v[32:33], v[48:49] op_sel_hi:[1,0]
	v_pk_mul_f32 v[40:41], v[40:41], v[48:49] op_sel_hi:[1,0]
	v_pk_mul_f32 v[36:37], v[34:35], v[44:45]
	v_pk_mul_f32 v[34:35], v[32:33], v[46:47]
	v_pk_mul_f32 v[40:41], v[40:41], v[54:55]
	v_cvt_pk_bf16_f32 v34, v34, v35
	v_cvt_pk_bf16_f32 v35, v36, v37
	v_add_u32_e32 v37, 0xc6000, v114
	v_mul_f32_e32 v36, 0xbfb8aa3b, v130
	v_rcp_f32_e32 v50, v50
	v_rcp_f32_e32 v51, v51
	v_cvt_pk_bf16_f32 v32, v40, v41
	v_pk_mul_f32 v[38:39], v[30:31], v[36:37] op_sel_hi:[1,0]
	v_pk_mul_f32 v[40:41], v[28:29], v[36:37] op_sel_hi:[1,0]
	v_pk_mul_f32 v[26:27], v[26:27], v[30:31]
	v_pk_mul_f32 v[24:25], v[24:25], v[28:29]
	v_pk_mul_f32 v[28:29], v[22:23], v[36:37] op_sel_hi:[1,0]
	v_pk_mul_f32 v[30:31], v[20:21], v[36:37] op_sel_hi:[1,0]
	v_exp_f32_e32 v28, v28
	v_exp_f32_e32 v30, v30
	v_exp_f32_e32 v29, v29
	v_exp_f32_e32 v31, v31
	v_exp_f32_e32 v40, v40
	v_exp_f32_e32 v38, v38
	v_exp_f32_e32 v39, v39
	v_exp_f32_e32 v41, v41
	v_pk_mul_f32 v[42:43], v[42:43], v[48:49] op_sel_hi:[1,0]
	v_pk_add_f32 v[28:29], v[28:29], 1.0 op_sel_hi:[1,0]
	v_pk_mul_f32 v[42:43], v[42:43], v[50:51]
	v_pk_add_f32 v[30:31], v[30:31], 1.0 op_sel_hi:[1,0]
	v_cvt_pk_bf16_f32 v33, v42, v43
	global_store_dwordx4 v37, v[32:35], s[24:25]
	v_rcp_f32_e32 v30, v30
	v_rcp_f32_e32 v31, v31
	v_pk_add_f32 v[34:35], v[38:39], 1.0 op_sel_hi:[1,0]
	v_pk_add_f32 v[38:39], v[40:41], 1.0 op_sel_hi:[1,0]
	v_rcp_f32_e32 v28, v28
	v_rcp_f32_e32 v29, v29
	v_rcp_f32_e32 v38, v38
	v_rcp_f32_e32 v39, v39
	v_mul_f32_e32 v32, v130, v130
	v_pk_mul_f32 v[18:19], v[18:19], v[22:23]
	v_pk_mul_f32 v[16:17], v[16:17], v[20:21]
	v_pk_mul_f32 v[18:19], v[18:19], v[32:33] op_sel_hi:[1,0]
	v_pk_mul_f32 v[16:17], v[16:17], v[32:33] op_sel_hi:[1,0]
	v_pk_mul_f32 v[24:25], v[24:25], v[32:33] op_sel_hi:[1,0]
	v_pk_mul_f32 v[20:21], v[18:19], v[28:29]
	v_pk_mul_f32 v[18:19], v[16:17], v[30:31]
	v_rcp_f32_e32 v34, v34
	v_rcp_f32_e32 v35, v35
	v_pk_mul_f32 v[24:25], v[24:25], v[38:39]
	v_cvt_pk_bf16_f32 v18, v18, v19
	v_cvt_pk_bf16_f32 v19, v20, v21
	v_add_u32_e32 v21, 0xdc000, v114
	v_mul_f32_e32 v20, 0xbfb8aa3b, v131
	v_cvt_pk_bf16_f32 v16, v24, v25
	v_pk_mul_f32 v[22:23], v[14:15], v[20:21] op_sel_hi:[1,0]
	v_pk_mul_f32 v[24:25], v[12:13], v[20:21] op_sel_hi:[1,0]
	v_pk_mul_f32 v[10:11], v[10:11], v[14:15]
	v_pk_mul_f32 v[8:9], v[8:9], v[12:13]
	v_pk_mul_f32 v[12:13], v[6:7], v[20:21] op_sel_hi:[1,0]
	v_pk_mul_f32 v[14:15], v[4:5], v[20:21] op_sel_hi:[1,0]
	v_exp_f32_e32 v24, v24
	v_exp_f32_e32 v22, v22
	v_exp_f32_e32 v23, v23
	v_exp_f32_e32 v25, v25
	v_exp_f32_e32 v14, v14
	v_exp_f32_e32 v12, v12
	v_exp_f32_e32 v13, v13
	v_exp_f32_e32 v15, v15
	v_pk_mul_f32 v[26:27], v[26:27], v[32:33] op_sel_hi:[1,0]
	v_pk_mul_f32 v[2:3], v[2:3], v[6:7]
	v_pk_mul_f32 v[26:27], v[26:27], v[34:35]
	v_pk_add_f32 v[12:13], v[12:13], 1.0 op_sel_hi:[1,0]
	v_cvt_pk_bf16_f32 v17, v26, v27
	global_store_dwordx4 v21, v[16:19], s[24:25]
	v_pk_add_f32 v[14:15], v[14:15], 1.0 op_sel_hi:[1,0]
	v_rcp_f32_e32 v12, v12
	v_pk_add_f32 v[18:19], v[22:23], 1.0 op_sel_hi:[1,0]
	v_pk_add_f32 v[22:23], v[24:25], 1.0 op_sel_hi:[1,0]
	v_rcp_f32_e32 v18, v18
	v_rcp_f32_e32 v22, v22
	v_rcp_f32_e32 v23, v23
	v_rcp_f32_e32 v19, v19
	v_rcp_f32_e32 v14, v14
	v_rcp_f32_e32 v15, v15
	v_rcp_f32_e32 v13, v13
	v_mul_f32_e32 v16, v131, v131
	v_pk_mul_f32 v[0:1], v[0:1], v[4:5]
	v_pk_mul_f32 v[8:9], v[8:9], v[16:17] op_sel_hi:[1,0]
	v_pk_mul_f32 v[10:11], v[10:11], v[16:17] op_sel_hi:[1,0]
	v_pk_mul_f32 v[0:1], v[0:1], v[16:17] op_sel_hi:[1,0]
	v_pk_mul_f32 v[2:3], v[2:3], v[16:17] op_sel_hi:[1,0]
	v_pk_mul_f32 v[10:11], v[10:11], v[18:19]
	v_pk_mul_f32 v[8:9], v[8:9], v[22:23]
	v_pk_mul_f32 v[4:5], v[2:3], v[12:13]
	v_pk_mul_f32 v[2:3], v[0:1], v[14:15]
	v_cvt_pk_bf16_f32 v0, v8, v9
	v_cvt_pk_bf16_f32 v1, v10, v11
	v_cvt_pk_bf16_f32 v2, v2, v3
	v_cvt_pk_bf16_f32 v3, v4, v5
	v_add_u32_e32 v4, 0xf2000, v114
	s_andn2_b64 vcc, exec, s[38:39]
	s_mov_b64 s[28:29], -1
	global_store_dwordx4 v4, v[0:3], s[24:25]
	s_cbranch_vccnz .LBB0_80
	s_andn2_b64 vcc, exec, s[44:45]
	s_cbranch_vccnz .LBB0_79
	s_barrier
	s_branch .LBB0_79

; __device__ __forceinline__ float bf_lo(unsigned w) { return (float)__builtin_bit_cast(h16x2, w).x; }
; __device__ __forceinline__ float bf_hi(unsigned w) { return (float)__builtin_bit_cast(h16x2, w).y; }
; __device__ __forceinline__ float bf_lo(unsigned w) { return __uint_as_float(w << 16); }
; __device__ __forceinline__ float bf_hi(unsigned w) { return __uint_as_float(w & 0xffff0000u); }
; __device__ __forceinline__ void conv4_phase(const bf16_t* urec, bf16_t* xc, const float* cw, const float* cb, int tid, int G) {
;     ...
;     for (int it = gt; it < (MTOK / 16) * 128; it += NT) {
;         const int cgp = it & 127, run = it >> 7, t0 = run * 16, c0 = cgp * 8;
;         float w[4][8], b[8], x0[8], x1[8], x2[8];
; #pragma unroll
;         for (int k = 0; k < 4; ++k) { const f32x4 a = *(const f32x4*)(cw + k * DM + c0), bq = *(const f32x4*)(cw + k * DM + c0 + 4);
; #pragma unroll
;             for (int j = 0; j < 4; ++j) { w[k][j] = a[j]; w[k][4 + j] = bq[j]; } }
;         { const f32x4 a = *(const f32x4*)(cb + c0), bq = *(const f32x4*)(cb + c0 + 4);
; #pragma unroll
;             for (int j = 0; j < 4; ++j) { b[j] = a[j]; b[4 + j] = bq[j]; } }
; #pragma unroll
;         for (int j = 0; j < 8; ++j) { x0[j] = 0.f; x1[j] = 0.f; x2[j] = 0.f; }
;         if ((t0 & (SEQ - 1)) != 0) {
;             const u32x4 a = *(const u32x4*)(urec + (size_t)(t0 - 3) * DM + c0), bq = *(const u32x4*)(urec + (size_t)(t0 - 2) * DM + c0), cq = *(const u32x4*)(urec + (size_t)(t0 - 1) * DM + c0);
; #pragma unroll
;             for (int j = 0; j < 4; ++j) { x0[2 * j] = bf_lo(a[j]); x0[2 * j + 1] = bf_hi(a[j]); x1[2 * j] = bf_lo(bq[j]); x1[2 * j + 1] = bf_hi(bq[j]); x2[2 * j] = bf_lo(cq[j]); x2[2 * j + 1] = bf_hi(cq[j]); }
.LBB0_245:
	v_lshlrev_b32_e32 v0, 3, v74
	v_and_b32_e32 v66, 0x3f8, v0
	v_lshlrev_b32_e32 v36, 2, v66
	v_mov_b32_e32 v37, v80
	v_lshl_add_u64 v[24:25], s[38:39], 0, v[36:37]
	v_add_co_u32_e32 v8, vcc, 0x1000, v24
	s_mov_b64 s[22:23], 0x1000
	s_nop 0
	v_addc_co_u32_e32 v9, vcc, 0, v25, vcc
	v_lshl_add_u64 v[12:13], v[24:25], 0, s[22:23]
	s_mov_b64 s[22:23], 0x2000
	v_add_co_u32_e32 v16, vcc, s33, v24
	v_lshl_add_u64 v[20:21], v[24:25], 0, s[22:23]
	s_nop 0
	v_addc_co_u32_e32 v17, vcc, 0, v25, vcc
	s_mov_b64 s[22:23], 0x3000
	v_lshl_add_u64 v[28:29], v[24:25], 0, s[22:23]
	v_add_co_u32_e32 v24, vcc, 0x3000, v24
	global_load_dwordx4 v[0:3], v36, s[38:39] offset:16
	global_load_dwordx4 v[4:7], v36, s[38:39]
	v_addc_co_u32_e32 v25, vcc, 0, v25, vcc
	global_load_dwordx4 v[8:11], v[8:9], off
	s_nop 0
	global_load_dwordx4 v[12:15], v[12:13], off offset:16
	s_nop 0
	global_load_dwordx4 v[16:19], v[16:17], off
	s_nop 0
	global_load_dwordx4 v[20:23], v[20:21], off offset:16
	s_nop 0
	global_load_dwordx4 v[24:27], v[24:25], off
	s_nop 0
	global_load_dwordx4 v[28:31], v[28:29], off offset:16
	s_nop 0
	global_load_dwordx4 v[32:35], v36, s[40:41] offset:16
	s_nop 0
	global_load_dwordx4 v[36:39], v36, s[40:41]
	v_ashrrev_i32_e32 v40, 3, v74
	v_and_b32_e32 v40, -16, v40
	v_bfe_u32 v42, v40, 11, 3
	v_lshrrev_b32_e32 v43, 14, v40
	v_xor_b32_e32 v43, 3, v43
	v_and_b32_e32 v40, 0x7ff, v40
	v_lshl_or_b32 v40, v42, 13, v40
	v_lshl_or_b32 v40, v43, 11, v40
	v_and_b32_e32 v41, 0x3f80, v74
	v_mov_b32_e32 v81, v80
	v_cmp_ne_u32_e32 vcc, 0, v41
	v_ashrrev_i32_e32 v41, 31, v40
	v_mov_b64_e32 v[42:43], v[80:81]
	v_mov_b64_e32 v[50:51], v[80:81]
	v_mov_b64_e32 v[58:59], v[80:81]
	v_mov_b64_e32 v[44:45], v[80:81]
	v_mov_b64_e32 v[52:53], v[80:81]
	v_mov_b64_e32 v[60:61], v[80:81]
	v_mov_b64_e32 v[46:47], v[80:81]
	v_mov_b64_e32 v[54:55], v[80:81]
	v_mov_b64_e32 v[62:63], v[80:81]
	v_mov_b64_e32 v[48:49], v[80:81]
	v_mov_b64_e32 v[56:57], v[80:81]
	v_mov_b64_e32 v[64:65], v[80:81]
	s_and_saveexec_b64 s[28:29], vcc
	s_cbranch_execz .LBB0_247
	v_lshlrev_b64 v[44:45], 11, v[40:41]
	v_lshlrev_b32_e32 v42, 1, v66
	v_mov_b32_e32 v43, v80
	v_lshl_add_u64 v[44:45], s[46:47], 0, v[44:45]
	v_lshl_add_u64 v[42:43], v[44:45], 0, v[42:43]
	global_load_dwordx4 v[58:61], v[42:43], off offset:-4096
	global_load_dwordx4 v[64:67], v[42:43], off offset:-2048
	v_add_co_u32_e32 v42, vcc, 0xfffff000, v42
	s_waitcnt vmcnt(1)
	v_lshlrev_b32_e32 v56, 16, v58
	v_addc_co_u32_e32 v43, vcc, -1, v43, vcc
	global_load_dwordx4 v[68:71], v[42:43], off offset:-2048
	v_and_b32_e32 v57, 0xffff0000, v58
	s_waitcnt vmcnt(1)
	v_lshlrev_b32_e32 v48, 16, v64
	v_and_b32_e32 v49, 0xffff0000, v64
	v_lshlrev_b32_e32 v54, 16, v59
	v_and_b32_e32 v55, 0xffff0000, v59
	v_lshlrev_b32_e32 v46, 16, v65
	v_and_b32_e32 v47, 0xffff0000, v65
	v_lshlrev_b32_e32 v52, 16, v60
	v_and_b32_e32 v53, 0xffff0000, v60
	v_lshlrev_b32_e32 v44, 16, v66
	v_and_b32_e32 v45, 0xffff0000, v66
	v_lshlrev_b32_e32 v50, 16, v61
	v_and_b32_e32 v51, 0xffff0000, v61
	v_lshlrev_b32_e32 v42, 16, v67
	v_and_b32_e32 v43, 0xffff0000, v67
	s_waitcnt vmcnt(0)
	v_lshlrev_b32_e32 v64, 16, v68
	v_and_b32_e32 v65, 0xffff0000, v68
	v_lshlrev_b32_e32 v62, 16, v69
	v_and_b32_e32 v63, 0xffff0000, v69
	v_lshlrev_b32_e32 v60, 16, v70
	v_and_b32_e32 v61, 0xffff0000, v70
	v_lshlrev_b32_e32 v58, 16, v71
	v_and_b32_e32 v59, 0xffff0000, v71

; __device__ __forceinline__ void scan_phase(LAS unsigned char* lds, const bf16_t* om, const bf16_t* bx, const bf16_t* gate, bf16_t* y, int tid, int G) {
;     ...
;     for (int item = blockIdx.x; item < 512; item += G) {
;         const int b = item >> 4, cgp = item & 15;
;         const unsigned base = (unsigned)(((b * SEQ + chunk * 64) * DM + cgp * 64 + cq * 4) * 2);
;         float P[4] = {1.f, 1.f, 1.f, 1.f}, S[4] = {0.f, 0.f, 0.f, 0.f};
.LBB0_382:
	s_lshr_b32 s2, s31, 11
	s_and_b32 s23, s2, 7
	s_lshr_b32 s2, s2, 3
	s_xor_b32 s2, s2, 3
	s_lshl_b32 s23, s23, 2
	s_or_b32 s2, s2, s23
	s_lshl_b32 s2, s2, 21
	s_and_b32 s22, s30, 0x3c0
	s_or_b32 s2, s22, s2
	v_add_lshl_u32 v8, s2, v20, 1
	v_mov_b32_e32 v9, v80
	v_mov_b32_e32 v11, 0
	v_mov_b32_e32 v0, 1.0
	s_mov_b32 s2, -8
	s_mov_b64 s[26:27], 0
	s_mov_b64 s[28:29], s[88:89]
	v_mov_b32_e32 v2, 1.0
	v_mov_b32_e32 v4, 1.0
	v_mov_b32_e32 v6, 1.0
	v_mov_b32_e32 v17, 0
	v_mov_b32_e32 v15, 0
	v_mov_b32_e32 v13, 0
